# h3-DA-bias-reads-issued-between-QK-MFMAs-both-units
# speedup vs baseline: 1.0229x; 1.0184x over previous
; #define LAS __attribute__((address_space(3)))
; #define GAS __attribute__((address_space(1)))
; template <int MODE> ...
;     ...
;         __syncthreads();
;         const bool more = kt < kt_hi;
;         if (more) {
;             const int kv1 = 64 * (kt + 1);
;             kr0 = *(const GAS u32x4*)(ksrc + (tok0 + (size_t)(kv1 + kp_row0) * dil) * 2048);
;             kr1 = *(const GAS u32x4*)(ksrc + (tok0 + (size_t)(kv1 + kp_row0 + 32) * dil) * 2048);
;             vr0 = *(const GAS u32x4*)(vsrc + kv1);
;             vr1 = *(const GAS u32x4*)(vsrc + (size_t)64 * TOK + kv1);
;             asm volatile("" ::: "memory");
;         }
;         const int kv0 = 64 * kt;
;         bool skip = kv0 > q_lo + 31;
;         if (MODE == 1) skip = skip || (kv0 + 63 < q_lo - 128);
;         if (!skip) {
;             const LAS unsigned char* kb = lds + bufsel * AT_BUF; const LAS unsigned char* vb = kb + AT_KBYTES;
;             f32x16 s0, s1;
; #pragma unroll
;             for (int r = 0; r < 16; ++r) { s0[r] = 0.f; s1[r] = 0.f; }
;             {
;                 bf16x8 ka[4], kc[4];
; #pragma unroll
;                 for (int ds = 0; ds < 4; ++ds) {
;                     ka[ds] = *(const LAS bf16x8*)(kb + r32 * AT_KROW + mp * 128 + (16 * ds + 8 * hi) * 2);
;                     kc[ds] = *(const LAS bf16x8*)(kb + (32 + r32) * AT_KROW + mp * 128 + (16 * ds + 8 * hi) * 2);
;                 }
;                 __builtin_amdgcn_sched_barrier(0);
; #pragma unroll
;                 for (int ds = 0; ds < 4; ++ds) {
;                     s0 = __builtin_amdgcn_mfma_f32_32x32x16_bf16(ka[ds], qf[ds], s0, 0, 0, 0);
;                     s1 = __builtin_amdgcn_mfma_f32_32x32x16_bf16(kc[ds], qf[ds], s1, 0, 0, 0);
;                 }
;             }
;             const int relbase = qi - kv0 - 4 * hi;
;             constexpr int cmax = (MODE == 0) ? 2047 : 128;
;             float mx = -1e30f;
;             bool interior = (kv0 + 63 <= q_lo);
;             if (MODE == 1) interior = interior && (q_lo + 31 - kv0 <= 128);
;             if (interior) {
;                 const LAS float* p = biasL + mp * 2048 + (relbase - 59);
; #pragma unroll
;                 for (int r = 0; r < 16; ++r) {
;                     const int o = 59 - ((r & 3) + 8 * (r >> 2));
;                     s0[r] += p[o]; s1[r] += p[o - 32];
;                     mx = fmaxf(mx, fmaxf(s0[r], s1[r]));
;                 }
.LBB0_381:
	v_lshl_add_u64 v[2:3], s[54:55], 0, v[144:145]
	v_add_co_u32_e32 v4, vcc, s90, v2
	v_lshl_add_u64 v[10:11], s[54:55], 0, v[142:143]
	s_nop 0
	v_addc_co_u32_e32 v5, vcc, 0, v3, vcc
	v_add_co_u32_e32 v6, vcc, s91, v2
	s_waitcnt lgkmcnt(0)
	s_nop 0
	v_addc_co_u32_e32 v7, vcc, 0, v3, vcc
	v_add_co_u32_e32 v12, vcc, 0x20000000, v10
	s_barrier
	s_nop 0
	v_addc_co_u32_e32 v13, vcc, 0, v11, vcc
	v_add_co_u32_e32 v14, vcc, 0x20800000, v10
	global_load_dwordx4 v[2:5], v[4:5], off offset:2048
	s_nop 0
	global_load_dwordx4 v[6:9], v[6:7], off offset:2048
	v_addc_co_u32_e32 v15, vcc, 0, v11, vcc
	global_load_dwordx4 v[10:13], v[12:13], off offset:128
	s_nop 0
	global_load_dwordx4 v[128:131], v[14:15], off offset:128
	s_and_b32 s29, s25, 1
	s_add_i32 s28, s14, 64
	s_cmp_gt_u32 s28, s26
	s_cbranch_scc1 .LBB0_387
	s_mul_i32 s15, s29, 0x8800
	s_add_i32 s30, s15, 0
	s_add_i32 s15, s27, s30
	v_add3_u32 v0, s15, v197, v136
	ds_read_b128 v[80:83], v0
	ds_read_b128 v[148:151], v0 offset:32
	ds_read_b128 v[84:87], v0 offset:8704
	ds_read_b128 v[152:155], v0 offset:8736
	ds_read_b128 v[156:159], v0 offset:64
	ds_read_b128 v[160:163], v0 offset:96
	ds_read_b128 v[164:167], v0 offset:8768
	ds_read_b128 v[168:171], v0 offset:8800
	ds_read2_b32 v[14:15], v200 offset0:58 offset1:59
	ds_read2_b32 v[218:219], v200 offset0:26 offset1:27
	ds_read2_b32 v[220:221], v200 offset0:24 offset1:25
	ds_read2_b32 v[222:223], v200 offset0:56 offset1:57
	ds_read2_b32 v[224:225], v200 offset0:50 offset1:51
	ds_read2_b32 v[174:175], v200 offset0:18 offset1:19
	ds_read2_b32 v[226:227], v200 offset0:48 offset1:49
	s_waitcnt lgkmcnt(14)
	v_mfma_f32_32x32x16_bf16 v[96:111], v[80:83], v[124:127], 0
	s_add_i32 s31, s14, 0x7f
	s_mov_b64 s[14:15], -1
	s_cmp_gt_u32 s31, s24
	ds_read2_b32 v[172:173], v200 offset0:16 offset1:17
	s_waitcnt lgkmcnt(13)
	v_mfma_f32_32x32x16_bf16 v[80:95], v[84:87], v[124:127], 0
	v_mfma_f32_32x32x16_bf16 v[96:111], v[148:151], v[120:123], v[96:111]
	ds_read2_b32 v[242:243], v200 offset0:42 offset1:43
	ds_read2_b32 v[182:183], v200 offset0:10 offset1:11
	s_waitcnt lgkmcnt(14)
	v_mfma_f32_32x32x16_bf16 v[80:95], v[152:155], v[120:123], v[80:95]
	ds_read2_b32 v[176:177], v200 offset0:40 offset1:41
	s_waitcnt lgkmcnt(14)
	v_mfma_f32_32x32x16_bf16 v[96:111], v[156:159], v[116:119], v[96:111]
	ds_read2_b32 v[184:185], v200 offset0:8 offset1:9
	s_waitcnt lgkmcnt(13)
	v_mfma_f32_32x32x16_bf16 v[80:95], v[164:167], v[116:119], v[80:95]
	v_mfma_f32_32x32x16_bf16 v[96:111], v[160:163], v[112:115], v[96:111]
	ds_read2_b32 v[180:181], v200 offset0:34 offset1:35
	ds_read2_b32 v[188:189], v200 offset0:2 offset1:3
	s_waitcnt lgkmcnt(14)
	v_mfma_f32_32x32x16_bf16 v[80:95], v[168:171], v[112:115], v[80:95]
	ds_read2_b32 v[178:179], v200 offset0:32 offset1:33
	s_nop 11
	s_cbranch_scc1 .LdaA_bias_masked
	s_waitcnt lgkmcnt(14)
	v_pk_add_f32 v[14:15], v[96:97], v[14:15] op_sel:[0,1] op_sel_hi:[1,0]
	ds_read2_b32 v[186:187], v200 offset0:0 offset1:1
	s_waitcnt lgkmcnt(14)
	v_pk_add_f32 v[166:167], v[80:81], v[218:219] op_sel:[0,1] op_sel_hi:[1,0]
	s_waitcnt lgkmcnt(13)
	v_pk_add_f32 v[168:169], v[82:83], v[220:221] op_sel:[0,1] op_sel_hi:[1,0]
	s_waitcnt lgkmcnt(12)
	v_pk_add_f32 v[148:149], v[98:99], v[222:223] op_sel:[0,1] op_sel_hi:[1,0]
	s_waitcnt lgkmcnt(11)
	v_pk_add_f32 v[152:153], v[100:101], v[224:225] op_sel:[0,1] op_sel_hi:[1,0]
	s_waitcnt lgkmcnt(10)
	v_pk_add_f32 v[174:175], v[84:85], v[174:175] op_sel:[0,1] op_sel_hi:[1,0]
	s_waitcnt lgkmcnt(9)
	v_pk_add_f32 v[150:151], v[102:103], v[226:227] op_sel:[0,1] op_sel_hi:[1,0]
	s_waitcnt lgkmcnt(8)
	v_pk_add_f32 v[172:173], v[86:87], v[172:173] op_sel:[0,1] op_sel_hi:[1,0]
	s_waitcnt lgkmcnt(7)
	v_pk_add_f32 v[170:171], v[104:105], v[242:243] op_sel:[0,1] op_sel_hi:[1,0]
	s_waitcnt lgkmcnt(6)
	v_pk_add_f32 v[182:183], v[88:89], v[182:183] op_sel:[0,1] op_sel_hi:[1,0]
	s_waitcnt lgkmcnt(5)
	v_pk_add_f32 v[176:177], v[106:107], v[176:177] op_sel:[0,1] op_sel_hi:[1,0]
	s_waitcnt lgkmcnt(4)
	v_pk_add_f32 v[184:185], v[90:91], v[184:185] op_sel:[0,1] op_sel_hi:[1,0]
	s_waitcnt lgkmcnt(3)
	v_pk_add_f32 v[180:181], v[108:109], v[180:181] op_sel:[0,1] op_sel_hi:[1,0]
	s_waitcnt lgkmcnt(2)
	v_pk_add_f32 v[188:189], v[92:93], v[188:189] op_sel:[0,1] op_sel_hi:[1,0]
	s_waitcnt lgkmcnt(1)
	v_pk_add_f32 v[178:179], v[110:111], v[178:179] op_sel:[0,1] op_sel_hi:[1,0]
	s_waitcnt lgkmcnt(0)
	v_pk_add_f32 v[186:187], v[94:95], v[186:187] op_sel:[0,1] op_sel_hi:[1,0]
	v_max_f32_e32 v80, v14, v166
	v_max_f32_e32 v81, v15, v167
	v_max3_f32 v82, v80, s84, v81
	v_max_f32_e32 v80, v168, v148
	v_max_f32_e32 v81, v169, v149
	v_max3_f32 v82, v82, v80, v81
	v_max_f32_e32 v80, v152, v174
	v_max_f32_e32 v81, v153, v175
	v_max3_f32 v82, v82, v80, v81
	v_max_f32_e32 v80, v150, v172
	v_max_f32_e32 v81, v151, v173
	v_max3_f32 v82, v82, v80, v81
	v_max_f32_e32 v80, v170, v182
	v_max_f32_e32 v81, v171, v183
	v_max3_f32 v82, v82, v80, v81
	v_max_f32_e32 v80, v176, v184
	v_max_f32_e32 v81, v177, v185
	v_max3_f32 v82, v82, v80, v81
	v_max_f32_e32 v80, v180, v188
	v_max_f32_e32 v81, v181, v189
	v_max3_f32 v82, v82, v80, v81
	v_max_f32_e32 v80, v178, v186
	v_max_f32_e32 v81, v179, v187
	v_max3_f32 v0, v82, v80, v81
	s_branch .LBB0_386
; #define LAS __attribute__((address_space(3)))
; __device__ __forceinline__ float max_x32(float v) { auto rr = __builtin_amdgcn_permlane32_swap(__float_as_uint(v), __float_as_uint(v), false, false); return fmaxf(__uint_as_float(rr[0]), __uint_as_float(rr[1])); }
; __device__ __forceinline__ float fast_exp2(float x) { return __builtin_amdgcn_exp2f(x); }
; template <int MODE> ...
;     ...
;             } else {
;                 const volatile LAS float* bl = (const volatile LAS float*)(biasL + mp * 2048);
;                 float bb0[16], bb1[16];
; #pragma unroll
;                 for (int r = 0; r < 16; ++r) {
;                     const int rel0 = relbase - ((r & 3) + 8 * (r >> 2));
;                     bb0[r] = bl[min(max(rel0, 0), cmax)]; bb1[r] = bl[min(max(rel0 - 32, 0), cmax)];
;                 }
; #pragma unroll
;                 for (int r = 0; r < 16; ++r) {
;                     const int rel0 = relbase - ((r & 3) + 8 * (r >> 2)), rel1 = rel0 - 32;
;                     bool ok0 = rel0 >= 0, ok1 = rel1 >= 0;
;                     if (MODE == 1) { ok0 = ok0 && (rel0 <= 128); ok1 = ok1 && (rel1 <= 128); }
;                     const float t0 = s0[r] + bb0[r], t1 = s1[r] + bb1[r];
;                     s0[r] = ok0 ? t0 : -1e30f; s1[r] = ok1 ? t1 : -1e30f;
;                     mx = fmaxf(mx, fmaxf(s0[r], s1[r]));
;                 }
;             }
;             mx = max_x32(mx);
;             const float mnew = fmaxf(mrun, mx);
;             const float alpha = fast_exp2(mrun - mnew);
;             mrun = mnew;
.LdaA_bias_masked:
	v_add_u32_e32 v0, s33, v199
	s_waitcnt lgkmcnt(14)
	v_pk_add_f32 v[14:15], v[96:97], v[14:15] op_sel:[0,1] op_sel_hi:[1,0]
	ds_read2_b32 v[186:187], v200 offset0:0 offset1:1
	v_cmp_lt_i32_e32 vcc, -1, v0
	v_cmp_lt_i32_e64 s[100:101], 0, v0
	s_nop 1
	v_cndmask_b32_e32 v14, v214, v14, vcc
	v_cndmask_b32_e64 v15, v214, v15, s[100:101]
	s_waitcnt lgkmcnt(14)
	v_pk_add_f32 v[166:167], v[80:81], v[218:219] op_sel:[0,1] op_sel_hi:[1,0]
	v_cmp_lt_i32_e32 vcc, 31, v0
	v_cmp_lt_i32_e64 s[100:101], 32, v0
	s_nop 1
	v_cndmask_b32_e32 v166, v214, v166, vcc
	v_cndmask_b32_e64 v167, v214, v167, s[100:101]
	s_waitcnt lgkmcnt(13)
	v_pk_add_f32 v[168:169], v[82:83], v[220:221] op_sel:[0,1] op_sel_hi:[1,0]
	v_cmp_lt_i32_e32 vcc, 33, v0
	v_cmp_lt_i32_e64 s[100:101], 34, v0
	s_nop 1
	v_cndmask_b32_e32 v168, v214, v168, vcc
	v_cndmask_b32_e64 v169, v214, v169, s[100:101]
	s_waitcnt lgkmcnt(12)
	v_pk_add_f32 v[148:149], v[98:99], v[222:223] op_sel:[0,1] op_sel_hi:[1,0]
	v_cmp_lt_i32_e32 vcc, 1, v0
	v_cmp_lt_i32_e64 s[100:101], 2, v0
	s_nop 1
	v_cndmask_b32_e32 v148, v214, v148, vcc
	v_cndmask_b32_e64 v149, v214, v149, s[100:101]
	s_waitcnt lgkmcnt(11)
	v_pk_add_f32 v[152:153], v[100:101], v[224:225] op_sel:[0,1] op_sel_hi:[1,0]
	v_cmp_lt_i32_e32 vcc, 7, v0
	v_cmp_lt_i32_e64 s[100:101], 8, v0
	s_nop 1
	v_cndmask_b32_e32 v152, v214, v152, vcc
	v_cndmask_b32_e64 v153, v214, v153, s[100:101]
	s_waitcnt lgkmcnt(10)
	v_pk_add_f32 v[174:175], v[84:85], v[174:175] op_sel:[0,1] op_sel_hi:[1,0]
	v_cmp_lt_i32_e32 vcc, 39, v0
	v_cmp_lt_i32_e64 s[100:101], 40, v0
	s_nop 1
	v_cndmask_b32_e32 v174, v214, v174, vcc
	v_cndmask_b32_e64 v175, v214, v175, s[100:101]
	s_waitcnt lgkmcnt(9)
	v_pk_add_f32 v[150:151], v[102:103], v[226:227] op_sel:[0,1] op_sel_hi:[1,0]
	v_cmp_lt_i32_e32 vcc, 9, v0
	v_cmp_lt_i32_e64 s[100:101], 10, v0
	s_nop 1
	v_cndmask_b32_e32 v150, v214, v150, vcc
	v_cndmask_b32_e64 v151, v214, v151, s[100:101]
	s_waitcnt lgkmcnt(8)
	v_pk_add_f32 v[172:173], v[86:87], v[172:173] op_sel:[0,1] op_sel_hi:[1,0]
	v_cmp_lt_i32_e32 vcc, 41, v0
	v_cmp_lt_i32_e64 s[100:101], 42, v0
	s_nop 1
	v_cndmask_b32_e32 v172, v214, v172, vcc
	v_cndmask_b32_e64 v173, v214, v173, s[100:101]
	s_waitcnt lgkmcnt(7)
	v_pk_add_f32 v[170:171], v[104:105], v[242:243] op_sel:[0,1] op_sel_hi:[1,0]
	v_cmp_lt_i32_e32 vcc, 15, v0
	v_cmp_lt_i32_e64 s[100:101], 16, v0
	s_nop 1
	v_cndmask_b32_e32 v170, v214, v170, vcc
	v_cndmask_b32_e64 v171, v214, v171, s[100:101]
	s_waitcnt lgkmcnt(6)
	v_pk_add_f32 v[182:183], v[88:89], v[182:183] op_sel:[0,1] op_sel_hi:[1,0]
	v_cmp_lt_i32_e32 vcc, 47, v0
	v_cmp_lt_i32_e64 s[100:101], 48, v0
	s_nop 1
	v_cndmask_b32_e32 v182, v214, v182, vcc
	v_cndmask_b32_e64 v183, v214, v183, s[100:101]
	s_waitcnt lgkmcnt(5)
	v_pk_add_f32 v[176:177], v[106:107], v[176:177] op_sel:[0,1] op_sel_hi:[1,0]
	v_cmp_lt_i32_e32 vcc, 17, v0
	v_cmp_lt_i32_e64 s[100:101], 18, v0
	s_nop 1
	v_cndmask_b32_e32 v176, v214, v176, vcc
	v_cndmask_b32_e64 v177, v214, v177, s[100:101]
	s_waitcnt lgkmcnt(4)
	v_pk_add_f32 v[184:185], v[90:91], v[184:185] op_sel:[0,1] op_sel_hi:[1,0]
	v_cmp_lt_i32_e32 vcc, 49, v0
	v_cmp_lt_i32_e64 s[100:101], 50, v0
	s_nop 1
	v_cndmask_b32_e32 v184, v214, v184, vcc
	v_cndmask_b32_e64 v185, v214, v185, s[100:101]
	s_waitcnt lgkmcnt(3)
	v_pk_add_f32 v[180:181], v[108:109], v[180:181] op_sel:[0,1] op_sel_hi:[1,0]
	v_cmp_lt_i32_e32 vcc, 23, v0
	v_cmp_lt_i32_e64 s[100:101], 24, v0
	s_nop 1
	v_cndmask_b32_e32 v180, v214, v180, vcc
	v_cndmask_b32_e64 v181, v214, v181, s[100:101]
	s_waitcnt lgkmcnt(2)
	v_pk_add_f32 v[188:189], v[92:93], v[188:189] op_sel:[0,1] op_sel_hi:[1,0]
	v_cmp_lt_i32_e32 vcc, 55, v0
	v_cmp_lt_i32_e64 s[100:101], 56, v0
	s_nop 1
	v_cndmask_b32_e32 v188, v214, v188, vcc
	v_cndmask_b32_e64 v189, v214, v189, s[100:101]
	s_waitcnt lgkmcnt(1)
	v_pk_add_f32 v[178:179], v[110:111], v[178:179] op_sel:[0,1] op_sel_hi:[1,0]
	v_cmp_lt_i32_e32 vcc, 25, v0
	v_cmp_lt_i32_e64 s[100:101], 26, v0
	s_nop 1
	v_cndmask_b32_e32 v178, v214, v178, vcc
	v_cndmask_b32_e64 v179, v214, v179, s[100:101]
	s_waitcnt lgkmcnt(0)
	v_pk_add_f32 v[186:187], v[94:95], v[186:187] op_sel:[0,1] op_sel_hi:[1,0]
	v_cmp_lt_i32_e32 vcc, 57, v0
	v_cmp_lt_i32_e64 s[100:101], 58, v0
	s_nop 1
	v_cndmask_b32_e32 v186, v214, v186, vcc
	v_cndmask_b32_e64 v187, v214, v187, s[100:101]
	v_max_f32_e32 v80, v14, v166
	v_max_f32_e32 v81, v15, v167
	v_max3_f32 v82, v80, s84, v81
	v_max_f32_e32 v80, v168, v148
	v_max_f32_e32 v81, v169, v149
	v_max3_f32 v82, v82, v80, v81
	v_max_f32_e32 v80, v152, v174
	v_max_f32_e32 v81, v153, v175
	v_max3_f32 v82, v82, v80, v81
	v_max_f32_e32 v80, v150, v172
	v_max_f32_e32 v81, v151, v173
	v_max3_f32 v82, v82, v80, v81
	v_max_f32_e32 v80, v170, v182
	v_max_f32_e32 v81, v171, v183
	v_max3_f32 v82, v82, v80, v81
	v_max_f32_e32 v80, v176, v184
	v_max_f32_e32 v81, v177, v185
	v_max3_f32 v82, v82, v80, v81
	v_max_f32_e32 v80, v180, v188
	v_max_f32_e32 v81, v181, v189
	v_max3_f32 v82, v82, v80, v81
	v_max_f32_e32 v80, v178, v186
	v_max_f32_e32 v81, v179, v187
	v_max3_f32 v0, v82, v80, v81
.LBB0_386:
	s_nop 8
	v_mov_b32_e32 v80, v0
	s_nop 1
	v_permlane32_swap_b32_e32 v0, v80
	v_max3_f32 v83, v198, v0, v80
	v_max_f32_e32 v211, v0, v80
	v_sub_f32_e32 v211, v211, v198
	v_cmp_lt_f32_e64 s[100:101], 4.0, v211
	s_nop 1
	s_cmp_eq_u64 s[100:101], 0
	s_cbranch_scc0 .Lresc_keep_A
	v_mov_b32_e32 v83, v198
; __device__ __forceinline__ unsigned cvt_pk_bf16(float lo, float hi) { f32x2_t v = {lo, hi}; bf16x2_t b = __builtin_convertvector(v, bf16x2_t); return __builtin_bit_cast(unsigned, b); }
; __device__ __forceinline__ float fast_exp2(float x) { return __builtin_amdgcn_exp2f(x); }
; template <int MODE> ...
;     ...
;             const float mnew = fmaxf(mrun, mx);
;             const float alpha = fast_exp2(mrun - mnew);
;             mrun = mnew;
;             float ps = 0.f;
; #pragma unroll
;             for (int r = 0; r < 16; ++r) { s0[r] = fast_exp2(s0[r] - mnew); s1[r] = fast_exp2(s1[r] - mnew); ps += s0[r] + s1[r]; }
;             lsum = lsum * alpha + ps;
; #pragma unroll
;             for (int i = 0; i < NDV; ++i)
; #pragma unroll
;                 for (int r = 0; r < 16; ++r) acc[i][r] *= alpha;
;             bf16x8 pf[2][2];
; #pragma unroll
;             for (int t = 0; t < 2; ++t) {
;                 u32x4 w0, w1;
;                 w0.x = cvt_pk_bf16(s0[8 * t + 0], s0[8 * t + 1]); w0.y = cvt_pk_bf16(s0[8 * t + 2], s0[8 * t + 3]); w0.z = cvt_pk_bf16(s0[8 * t + 4], s0[8 * t + 5]); w0.w = cvt_pk_bf16(s0[8 * t + 6], s0[8 * t + 7]);
;                 w1.x = cvt_pk_bf16(s1[8 * t + 0], s1[8 * t + 1]); w1.y = cvt_pk_bf16(s1[8 * t + 2], s1[8 * t + 3]); w1.z = cvt_pk_bf16(s1[8 * t + 4], s1[8 * t + 5]); w1.w = cvt_pk_bf16(s1[8 * t + 6], s1[8 * t + 7]);
;                 pf[0][t] = __builtin_bit_cast(bf16x8, w0); pf[1][t] = __builtin_bit_cast(bf16x8, w1);
;             }
;     ...
;             {
;                 bf16x8 vcur[4], vnxt[4];
;                 AT_LOADV(vcur, 0);
; #pragma unroll
;                 for (int dvb = 0; dvb < NDV; ++dvb) {
;                     if (dvb + 1 < NDV) AT_LOADV(vnxt, dvb + 1);
;                     __builtin_amdgcn_sched_barrier(0);
; #pragma unroll
;                     for (int i = 0; i < 4; ++i) acc[dvb] = __builtin_amdgcn_mfma_f32_32x32x16_bf16(vcur[i], pf[i >> 1][i & 1], acc[dvb], 0, 0, 0);
.Lresc_keep_A:
	v_sub_f32_e32 v85, v152, v83
	v_exp_f32_e32 v152, v85
	v_sub_f32_e32 v85, v174, v83
	v_exp_f32_e32 v156, v85
	v_sub_f32_e32 v85, v153, v83
	v_exp_f32_e32 v88, v85
	v_sub_f32_e32 v85, v175, v83
	v_exp_f32_e32 v86, v85
	v_sub_f32_e32 v85, v150, v83
	v_exp_f32_e32 v150, v85
	v_sub_f32_e32 v85, v172, v83
	v_exp_f32_e32 v153, v85
	v_sub_f32_e32 v85, v151, v83
	v_exp_f32_e32 v92, v85
	v_sub_f32_e32 v85, v173, v83
	v_exp_f32_e32 v90, v85
	v_sub_f32_e32 v85, v170, v83
	v_exp_f32_e32 v151, v85
	v_sub_f32_e32 v85, v182, v83
	v_exp_f32_e32 v157, v85
	v_sub_f32_e32 v85, v171, v83
	v_exp_f32_e32 v96, v85
	v_sub_f32_e32 v85, v183, v83
	v_exp_f32_e32 v94, v85
	v_sub_f32_e32 v85, v176, v83
	v_exp_f32_e32 v158, v85
	v_sub_f32_e32 v85, v184, v83
	v_exp_f32_e32 v159, v85
	v_sub_f32_e32 v85, v177, v83
	v_sub_f32_e32 v0, v14, v83
	v_exp_f32_e32 v100, v85
	v_sub_f32_e32 v85, v185, v83
	v_exp_f32_e32 v110, v0
	v_sub_f32_e32 v0, v166, v83
	v_sub_f32_e32 v14, v167, v83
	v_exp_f32_e32 v98, v85
	v_sub_f32_e32 v85, v180, v83
	v_exp_f32_e32 v154, v0
	v_sub_f32_e32 v0, v15, v83
	v_exp_f32_e32 v80, v14
	v_sub_f32_e32 v14, v148, v83
	v_exp_f32_e32 v160, v85
	v_sub_f32_e32 v85, v188, v83
	v_exp_f32_e32 v0, v0
	v_exp_f32_e32 v111, v14
	v_sub_f32_e32 v14, v168, v83
	v_exp_f32_e32 v161, v85
	v_sub_f32_e32 v85, v181, v83
	v_exp_f32_e32 v155, v14
	v_sub_f32_e32 v14, v149, v83
	v_exp_f32_e32 v104, v85
	v_sub_f32_e32 v85, v189, v83
	v_exp_f32_e32 v84, v14
	v_sub_f32_e32 v14, v169, v83
	v_exp_f32_e32 v102, v85
	v_sub_f32_e32 v85, v178, v83
	v_add_f32_e32 v81, v154, v110
	v_exp_f32_e32 v14, v14
	v_exp_f32_e32 v162, v85
	v_sub_f32_e32 v85, v186, v83
	v_exp_f32_e32 v163, v85
	v_sub_f32_e32 v85, v179, v83
	v_pk_add_f32 v[108:109], v[80:81], v[0:1]
	v_exp_f32_e32 v148, v85
	v_sub_f32_e32 v85, v187, v83
	v_pk_add_f32 v[108:109], v[108:109], v[108:109] op_sel_hi:[0,1]
	v_add_f32_e32 v15, v155, v111
	v_exp_f32_e32 v106, v85
	v_mov_b32_e32 v85, v109
	v_pk_add_f32 v[108:109], v[14:15], v[84:85]
	v_add_f32_e32 v87, v156, v152
	v_pk_add_f32 v[108:109], v[108:109], v[108:109] op_sel_hi:[0,1]
	v_mov_b32_e32 v89, v109
	v_pk_add_f32 v[108:109], v[86:87], v[88:89]
	v_add_f32_e32 v91, v153, v150
	v_pk_add_f32 v[108:109], v[108:109], v[108:109] op_sel_hi:[0,1]
	v_mov_b32_e32 v93, v109
	v_pk_add_f32 v[108:109], v[90:91], v[92:93]
	v_add_f32_e32 v95, v157, v151
	v_pk_add_f32 v[108:109], v[108:109], v[108:109] op_sel_hi:[0,1]
	v_mov_b32_e32 v97, v109
	v_pk_add_f32 v[108:109], v[94:95], v[96:97]
	v_add_f32_e32 v99, v159, v158
	v_pk_add_f32 v[108:109], v[108:109], v[108:109] op_sel_hi:[0,1]
	v_mov_b32_e32 v101, v109
	v_pk_add_f32 v[108:109], v[98:99], v[100:101]
	v_add_f32_e32 v103, v161, v160
	v_pk_add_f32 v[108:109], v[108:109], v[108:109] op_sel_hi:[0,1]
	v_mov_b32_e32 v105, v109
	v_pk_add_f32 v[108:109], v[102:103], v[104:105]
	v_add_f32_e32 v107, v163, v162
	v_pk_add_f32 v[108:109], v[108:109], v[108:109] op_sel_hi:[0,1]
	v_mov_b32_e32 v149, v109
	v_pk_add_f32 v[108:109], v[106:107], v[148:149]
	v_cvt_pk_bf16_f32 v87, v153, v90
	v_add_f32_e32 v15, v108, v109
	v_cvt_pk_bf16_f32 v108, v110, v0
	v_add3_u32 v0, s30, v141, v192
	v_add_u32_e32 v0, 0x4000, v0
	v_cvt_pk_bf16_f32 v109, v111, v84
	v_cvt_pk_bf16_f32 v110, v152, v88
	v_cvt_pk_bf16_f32 v111, v150, v92
	v_cvt_pk_bf16_f32 v88, v151, v96
	v_cvt_pk_bf16_f32 v89, v158, v100
	v_cvt_pk_bf16_f32 v90, v160, v104
	v_cvt_pk_bf16_f32 v91, v162, v148
	v_cvt_pk_bf16_f32 v92, v157, v94
	v_cvt_pk_bf16_f32 v93, v159, v98
	v_cvt_pk_bf16_f32 v94, v161, v102
	v_cvt_pk_bf16_f32 v95, v163, v106
	ds_read2_b64 v[96:99], v0 offset0:128 offset1:130
	ds_read2_b64 v[100:103], v0 offset0:132 offset1:134
	ds_read2_b64 v[104:107], v0 offset0:136 offset1:138
	ds_read2_b64 v[148:151], v0 offset0:140 offset1:142
	v_add3_u32 v0, s30, v192, v141
	v_cvt_pk_bf16_f32 v85, v155, v14
	v_add_u32_e32 v14, 0x5000, v0
	v_cvt_pk_bf16_f32 v84, v154, v80
	v_cvt_pk_bf16_f32 v86, v156, v86
	ds_read2_b64 v[152:155], v14 offset0:160 offset1:162
	ds_read2_b64 v[156:159], v14 offset0:164 offset1:166
	ds_read2_b64 v[160:163], v14 offset0:168 offset1:170
	ds_read2_b64 v[164:167], v14 offset0:172 offset1:174
	v_sub_f32_e32 v82, v198, v83
	v_exp_f32_e32 v82, v82
	s_nop 0
	s_cmp_eq_u64 s[100:101], 0
	s_cbranch_scc1 .Lresc_skip_A
	v_pk_mul_f32 v[78:79], v[78:79], v[82:83] op_sel_hi:[1,0]
	v_pk_mul_f32 v[76:77], v[76:77], v[82:83] op_sel_hi:[1,0]
	v_pk_mul_f32 v[74:75], v[74:75], v[82:83] op_sel_hi:[1,0]
	v_pk_mul_f32 v[72:73], v[72:73], v[82:83] op_sel_hi:[1,0]
	v_pk_mul_f32 v[70:71], v[70:71], v[82:83] op_sel_hi:[1,0]
	v_pk_mul_f32 v[68:69], v[68:69], v[82:83] op_sel_hi:[1,0]
	v_pk_mul_f32 v[66:67], v[66:67], v[82:83] op_sel_hi:[1,0]
	v_pk_mul_f32 v[64:65], v[64:65], v[82:83] op_sel_hi:[1,0]
	v_pk_mul_f32 v[62:63], v[62:63], v[82:83] op_sel_hi:[1,0]
	v_pk_mul_f32 v[60:61], v[60:61], v[82:83] op_sel_hi:[1,0]
	v_pk_mul_f32 v[58:59], v[58:59], v[82:83] op_sel_hi:[1,0]
	v_pk_mul_f32 v[56:57], v[56:57], v[82:83] op_sel_hi:[1,0]
	v_pk_mul_f32 v[54:55], v[54:55], v[82:83] op_sel_hi:[1,0]
	v_pk_mul_f32 v[52:53], v[52:53], v[82:83] op_sel_hi:[1,0]
	v_pk_mul_f32 v[50:51], v[50:51], v[82:83] op_sel_hi:[1,0]
	v_pk_mul_f32 v[48:49], v[48:49], v[82:83] op_sel_hi:[1,0]
	v_pk_mul_f32 v[46:47], v[46:47], v[82:83] op_sel_hi:[1,0]
	v_pk_mul_f32 v[44:45], v[44:45], v[82:83] op_sel_hi:[1,0]
	v_pk_mul_f32 v[42:43], v[42:43], v[82:83] op_sel_hi:[1,0]
	v_pk_mul_f32 v[40:41], v[40:41], v[82:83] op_sel_hi:[1,0]
	v_pk_mul_f32 v[38:39], v[38:39], v[82:83] op_sel_hi:[1,0]
	v_pk_mul_f32 v[36:37], v[36:37], v[82:83] op_sel_hi:[1,0]
	v_pk_mul_f32 v[34:35], v[34:35], v[82:83] op_sel_hi:[1,0]
	v_pk_mul_f32 v[32:33], v[32:33], v[82:83] op_sel_hi:[1,0]
	v_pk_mul_f32 v[30:31], v[30:31], v[82:83] op_sel_hi:[1,0]
	v_pk_mul_f32 v[28:29], v[28:29], v[82:83] op_sel_hi:[1,0]
	v_pk_mul_f32 v[26:27], v[26:27], v[82:83] op_sel_hi:[1,0]
	v_pk_mul_f32 v[24:25], v[24:25], v[82:83] op_sel_hi:[1,0]
	v_pk_mul_f32 v[22:23], v[22:23], v[82:83] op_sel_hi:[1,0]
	v_pk_mul_f32 v[20:21], v[20:21], v[82:83] op_sel_hi:[1,0]
	v_pk_mul_f32 v[18:19], v[18:19], v[82:83] op_sel_hi:[1,0]
	v_pk_mul_f32 v[16:17], v[16:17], v[82:83] op_sel_hi:[1,0]
; template <int MODE> ...
;     ...
;             {
;                 bf16x8 vcur[4], vnxt[4];
;                 AT_LOADV(vcur, 0);
; #pragma unroll
;                 for (int dvb = 0; dvb < NDV; ++dvb) {
;                     if (dvb + 1 < NDV) AT_LOADV(vnxt, dvb + 1);
;                     __builtin_amdgcn_sched_barrier(0);
; #pragma unroll
;                     for (int i = 0; i < 4; ++i) acc[dvb] = __builtin_amdgcn_mfma_f32_32x32x16_bf16(vcur[i], pf[i >> 1][i & 1], acc[dvb], 0, 0, 0);
;                     __builtin_amdgcn_sched_barrier(0);
; #pragma unroll
;                     for (int i = 0; i < 4; ++i) vcur[i] = vnxt[i];
;                 }
.Lresc_skip_A:
	s_waitcnt lgkmcnt(7)
	v_mfma_f32_32x32x16_bf16 v[64:79], v[96:99], v[108:111], v[64:79]
	s_waitcnt lgkmcnt(6)
	v_mfma_f32_32x32x16_bf16 v[64:79], v[100:103], v[88:91], v[64:79]
	s_waitcnt lgkmcnt(5)
	v_mfma_f32_32x32x16_bf16 v[64:79], v[104:107], v[84:87], v[64:79]
	s_waitcnt lgkmcnt(4)
	v_mfma_f32_32x32x16_bf16 v[64:79], v[148:151], v[92:95], v[64:79]
	v_add_u32_e32 v14, 0x6000, v0
	ds_read2_b64 v[96:99], v14 offset0:192 offset1:194
	ds_read2_b64 v[100:103], v14 offset0:196 offset1:198
	ds_read2_b64 v[104:107], v14 offset0:200 offset1:202
	ds_read2_b64 v[148:151], v14 offset0:204 offset1:206
	s_waitcnt lgkmcnt(7)
	v_mfma_f32_32x32x16_bf16 v[48:63], v[152:155], v[108:111], v[48:63]
	s_waitcnt lgkmcnt(6)
	v_mfma_f32_32x32x16_bf16 v[48:63], v[156:159], v[88:91], v[48:63]
	s_waitcnt lgkmcnt(5)
	v_mfma_f32_32x32x16_bf16 v[48:63], v[160:163], v[84:87], v[48:63]
	s_waitcnt lgkmcnt(4)
	v_mfma_f32_32x32x16_bf16 v[48:63], v[164:167], v[92:95], v[48:63]
	v_add_u32_e32 v0, 0x7000, v0
	ds_read2_b64 v[152:155], v0 offset0:224 offset1:226
	ds_read2_b64 v[156:159], v0 offset0:228 offset1:230
	ds_read2_b64 v[160:163], v0 offset0:232 offset1:234
	ds_read2_b64 v[164:167], v0 offset0:236 offset1:238
	s_waitcnt lgkmcnt(7)
	v_mfma_f32_32x32x16_bf16 v[32:47], v[96:99], v[108:111], v[32:47]
	s_waitcnt lgkmcnt(6)
	v_mfma_f32_32x32x16_bf16 v[32:47], v[100:103], v[88:91], v[32:47]
	s_waitcnt lgkmcnt(5)
	v_mfma_f32_32x32x16_bf16 v[32:47], v[104:107], v[84:87], v[32:47]
	s_waitcnt lgkmcnt(4)
	v_mfma_f32_32x32x16_bf16 v[32:47], v[148:151], v[92:95], v[32:47]
	s_waitcnt lgkmcnt(3)
	v_mfma_f32_32x32x16_bf16 v[16:31], v[152:155], v[108:111], v[16:31]
	s_waitcnt lgkmcnt(2)
	v_mfma_f32_32x32x16_bf16 v[16:31], v[156:159], v[88:91], v[16:31]
	s_waitcnt lgkmcnt(1)
	v_mfma_f32_32x32x16_bf16 v[16:31], v[160:163], v[84:87], v[16:31]
	s_waitcnt lgkmcnt(0)
	v_mfma_f32_32x32x16_bf16 v[16:31], v[164:167], v[92:95], v[16:31]
	v_fmac_f32_e32 v15, v139, v82
	v_mov_b32_e32 v198, v83
	v_mov_b32_e32 v139, v15

; #define LAS __attribute__((address_space(3)))
; #define GAS __attribute__((address_space(1)))
; template <int MODE> ...
;     ...
;         __syncthreads();
;         const bool more = kt < kt_hi;
;         if (more) {
;             const int kv1 = 64 * (kt + 1);
;             kr0 = *(const GAS u32x4*)(ksrc + (tok0 + (size_t)(kv1 + kp_row0) * dil) * 2048);
;             kr1 = *(const GAS u32x4*)(ksrc + (tok0 + (size_t)(kv1 + kp_row0 + 32) * dil) * 2048);
;             vr0 = *(const GAS u32x4*)(vsrc + kv1);
;             vr1 = *(const GAS u32x4*)(vsrc + (size_t)64 * TOK + kv1);
;             asm volatile("" ::: "memory");
;         }
;         const int kv0 = 64 * kt;
;         bool skip = kv0 > q_lo + 31;
;         if (MODE == 1) skip = skip || (kv0 + 63 < q_lo - 128);
;         if (!skip) {
;             const LAS unsigned char* kb = lds + bufsel * AT_BUF; const LAS unsigned char* vb = kb + AT_KBYTES;
;             f32x16 s0, s1;
; #pragma unroll
;             for (int r = 0; r < 16; ++r) { s0[r] = 0.f; s1[r] = 0.f; }
;             {
;                 bf16x8 ka[4], kc[4];
; #pragma unroll
;                 for (int ds = 0; ds < 4; ++ds) {
;                     ka[ds] = *(const LAS bf16x8*)(kb + r32 * AT_KROW + mp * 128 + (16 * ds + 8 * hi) * 2);
;                     kc[ds] = *(const LAS bf16x8*)(kb + (32 + r32) * AT_KROW + mp * 128 + (16 * ds + 8 * hi) * 2);
;                 }
;                 __builtin_amdgcn_sched_barrier(0);
; #pragma unroll
;                 for (int ds = 0; ds < 4; ++ds) {
;                     s0 = __builtin_amdgcn_mfma_f32_32x32x16_bf16(ka[ds], qf[ds], s0, 0, 0, 0);
;                     s1 = __builtin_amdgcn_mfma_f32_32x32x16_bf16(kc[ds], qf[ds], s1, 0, 0, 0);
;                 }
;             }
;             const int relbase = qi - kv0 - 4 * hi;
;             constexpr int cmax = (MODE == 0) ? 2047 : 128;
;             float mx = -1e30f;
;             bool interior = (kv0 + 63 <= q_lo);
;             if (MODE == 1) interior = interior && (q_lo + 31 - kv0 <= 128);
;             if (interior) {
;                 const LAS float* p = biasL + mp * 2048 + (relbase - 59);
; #pragma unroll
;                 for (int r = 0; r < 16; ++r) {
;                     const int o = 59 - ((r & 3) + 8 * (r >> 2));
;                     s0[r] += p[o]; s1[r] += p[o - 32];
;                     mx = fmaxf(mx, fmaxf(s0[r], s1[r]));
;                 }
.LBB0_402:
	v_lshl_add_u64 v[2:3], s[54:55], 0, v[144:145]
	v_add_co_u32_e32 v4, vcc, s90, v2
	v_lshl_add_u64 v[10:11], s[54:55], 0, v[142:143]
	s_nop 0
	v_addc_co_u32_e32 v5, vcc, 0, v3, vcc
	v_add_co_u32_e32 v6, vcc, s91, v2
	s_waitcnt lgkmcnt(0)
	s_nop 0
	v_addc_co_u32_e32 v7, vcc, 0, v3, vcc
	v_add_co_u32_e32 v12, vcc, 0x20000000, v10
	s_barrier
	s_nop 0
	v_addc_co_u32_e32 v13, vcc, 0, v11, vcc
	v_add_co_u32_e32 v14, vcc, 0x20800000, v10
	global_load_dwordx4 v[2:5], v[4:5], off offset:2048
	s_nop 0
	global_load_dwordx4 v[6:9], v[6:7], off offset:2048
	v_addc_co_u32_e32 v15, vcc, 0, v11, vcc
	global_load_dwordx4 v[10:13], v[12:13], off offset:128
	s_nop 0
	global_load_dwordx4 v[128:131], v[14:15], off offset:128
	s_and_b32 s9, s19, 1
	s_add_i32 s8, s0, 64
	s_cmp_gt_u32 s8, s21
	s_cbranch_scc1 .LBB0_408
	s_mul_i32 s1, s9, 0x8800
	s_add_i32 s12, s1, 0
	s_add_i32 s1, s20, s12
	v_add3_u32 v0, s1, v197, v140
	ds_read_b128 v[80:83], v0
	ds_read_b128 v[148:151], v0 offset:32
	ds_read_b128 v[84:87], v0 offset:8704
	ds_read_b128 v[152:155], v0 offset:8736
	ds_read_b128 v[156:159], v0 offset:64
	ds_read_b128 v[160:163], v0 offset:96
	ds_read_b128 v[164:167], v0 offset:8768
	ds_read_b128 v[168:171], v0 offset:8800
	ds_read2_b32 v[14:15], v202 offset0:58 offset1:59
	ds_read2_b32 v[218:219], v202 offset0:26 offset1:27
	ds_read2_b32 v[220:221], v202 offset0:56 offset1:57
	ds_read2_b32 v[222:223], v202 offset0:24 offset1:25
	ds_read2_b32 v[224:225], v202 offset0:50 offset1:51
	ds_read2_b32 v[174:175], v202 offset0:18 offset1:19
	ds_read2_b32 v[226:227], v202 offset0:48 offset1:49
	s_waitcnt lgkmcnt(14)
	s_waitcnt vmcnt(7)
	v_mfma_f32_32x32x16_bf16 v[96:111], v[80:83], v[124:127], 0
	s_add_i32 s13, s0, 0x7f
	s_mov_b64 s[0:1], -1
	s_cmp_gt_u32 s13, s15
	ds_read2_b32 v[172:173], v202 offset0:16 offset1:17
	s_waitcnt lgkmcnt(13)
	v_mfma_f32_32x32x16_bf16 v[80:95], v[84:87], v[124:127], 0
	s_waitcnt vmcnt(6)
	v_mfma_f32_32x32x16_bf16 v[96:111], v[148:151], v[120:123], v[96:111]
	ds_read2_b32 v[242:243], v202 offset0:42 offset1:43
	ds_read2_b32 v[182:183], v202 offset0:10 offset1:11
	s_waitcnt lgkmcnt(14)
	v_mfma_f32_32x32x16_bf16 v[80:95], v[152:155], v[120:123], v[80:95]
	ds_read2_b32 v[176:177], v202 offset0:40 offset1:41
	s_waitcnt lgkmcnt(14)
	s_waitcnt vmcnt(5)
	v_mfma_f32_32x32x16_bf16 v[96:111], v[156:159], v[116:119], v[96:111]
	ds_read2_b32 v[184:185], v202 offset0:8 offset1:9
	s_waitcnt lgkmcnt(13)
	v_mfma_f32_32x32x16_bf16 v[80:95], v[164:167], v[116:119], v[80:95]
	s_waitcnt vmcnt(4)
	v_mfma_f32_32x32x16_bf16 v[96:111], v[160:163], v[112:115], v[96:111]
	ds_read2_b32 v[180:181], v202 offset0:34 offset1:35
	ds_read2_b32 v[188:189], v202 offset0:2 offset1:3
	s_waitcnt lgkmcnt(14)
	v_mfma_f32_32x32x16_bf16 v[80:95], v[168:171], v[112:115], v[80:95]
	ds_read2_b32 v[178:179], v202 offset0:32 offset1:33
	s_nop 11
	s_cbranch_scc1 .LdaB_bias_masked
	s_waitcnt lgkmcnt(14)
	v_pk_add_f32 v[14:15], v[96:97], v[14:15] op_sel:[0,1] op_sel_hi:[1,0]
	ds_read2_b32 v[186:187], v202 offset0:0 offset1:1
	s_waitcnt lgkmcnt(14)
	v_pk_add_f32 v[166:167], v[80:81], v[218:219] op_sel:[0,1] op_sel_hi:[1,0]
	s_waitcnt lgkmcnt(13)
	v_pk_add_f32 v[148:149], v[98:99], v[220:221] op_sel:[0,1] op_sel_hi:[1,0]
	s_waitcnt lgkmcnt(12)
	v_pk_add_f32 v[168:169], v[82:83], v[222:223] op_sel:[0,1] op_sel_hi:[1,0]
	s_waitcnt lgkmcnt(11)
	v_pk_add_f32 v[152:153], v[100:101], v[224:225] op_sel:[0,1] op_sel_hi:[1,0]
	s_waitcnt lgkmcnt(10)
	v_pk_add_f32 v[174:175], v[84:85], v[174:175] op_sel:[0,1] op_sel_hi:[1,0]
	s_waitcnt lgkmcnt(9)
	v_pk_add_f32 v[150:151], v[102:103], v[226:227] op_sel:[0,1] op_sel_hi:[1,0]
	s_waitcnt lgkmcnt(8)
	v_pk_add_f32 v[172:173], v[86:87], v[172:173] op_sel:[0,1] op_sel_hi:[1,0]
	s_waitcnt lgkmcnt(7)
	v_pk_add_f32 v[170:171], v[104:105], v[242:243] op_sel:[0,1] op_sel_hi:[1,0]
	s_waitcnt lgkmcnt(6)
	v_pk_add_f32 v[182:183], v[88:89], v[182:183] op_sel:[0,1] op_sel_hi:[1,0]
	s_waitcnt lgkmcnt(5)
	v_pk_add_f32 v[176:177], v[106:107], v[176:177] op_sel:[0,1] op_sel_hi:[1,0]
	s_waitcnt lgkmcnt(4)
	v_pk_add_f32 v[184:185], v[90:91], v[184:185] op_sel:[0,1] op_sel_hi:[1,0]
	s_waitcnt lgkmcnt(3)
	v_pk_add_f32 v[180:181], v[108:109], v[180:181] op_sel:[0,1] op_sel_hi:[1,0]
	s_waitcnt lgkmcnt(2)
	v_pk_add_f32 v[188:189], v[92:93], v[188:189] op_sel:[0,1] op_sel_hi:[1,0]
	s_waitcnt lgkmcnt(1)
	v_pk_add_f32 v[178:179], v[110:111], v[178:179] op_sel:[0,1] op_sel_hi:[1,0]
	s_waitcnt lgkmcnt(0)
	v_pk_add_f32 v[186:187], v[94:95], v[186:187] op_sel:[0,1] op_sel_hi:[1,0]
	v_max_f32_e32 v80, v14, v166
	v_max_f32_e32 v81, v15, v167
	v_max3_f32 v82, v80, s84, v81
	v_max_f32_e32 v80, v148, v168
	v_max_f32_e32 v81, v149, v169
	v_max3_f32 v82, v82, v80, v81
	v_max_f32_e32 v80, v152, v174
	v_max_f32_e32 v81, v153, v175
	v_max3_f32 v82, v82, v80, v81
	v_max_f32_e32 v80, v150, v172
	v_max_f32_e32 v81, v151, v173
	v_max3_f32 v82, v82, v80, v81
	v_max_f32_e32 v80, v170, v182
	v_max_f32_e32 v81, v171, v183
	v_max3_f32 v82, v82, v80, v81
	v_max_f32_e32 v80, v176, v184
	v_max_f32_e32 v81, v177, v185
	v_max3_f32 v82, v82, v80, v81
	v_max_f32_e32 v80, v180, v188
	v_max_f32_e32 v81, v181, v189
	v_max3_f32 v82, v82, v80, v81
	v_max_f32_e32 v80, v178, v186
	v_max_f32_e32 v81, v179, v187
	v_max3_f32 v0, v82, v80, v81
	s_branch .LBB0_407
; #define LAS __attribute__((address_space(3)))
; __device__ __forceinline__ float max_x32(float v) { auto rr = __builtin_amdgcn_permlane32_swap(__float_as_uint(v), __float_as_uint(v), false, false); return fmaxf(__uint_as_float(rr[0]), __uint_as_float(rr[1])); }
; __device__ __forceinline__ float fast_exp2(float x) { return __builtin_amdgcn_exp2f(x); }
; template <int MODE> ...
;     ...
;             } else {
;                 const volatile LAS float* bl = (const volatile LAS float*)(biasL + mp * 2048);
;                 float bb0[16], bb1[16];
; #pragma unroll
;                 for (int r = 0; r < 16; ++r) {
;                     const int rel0 = relbase - ((r & 3) + 8 * (r >> 2));
;                     bb0[r] = bl[min(max(rel0, 0), cmax)]; bb1[r] = bl[min(max(rel0 - 32, 0), cmax)];
;                 }
; #pragma unroll
;                 for (int r = 0; r < 16; ++r) {
;                     const int rel0 = relbase - ((r & 3) + 8 * (r >> 2)), rel1 = rel0 - 32;
;                     bool ok0 = rel0 >= 0, ok1 = rel1 >= 0;
;                     if (MODE == 1) { ok0 = ok0 && (rel0 <= 128); ok1 = ok1 && (rel1 <= 128); }
;                     const float t0 = s0[r] + bb0[r], t1 = s1[r] + bb1[r];
;                     s0[r] = ok0 ? t0 : -1e30f; s1[r] = ok1 ? t1 : -1e30f;
;                     mx = fmaxf(mx, fmaxf(s0[r], s1[r]));
;                 }
;             }
;             mx = max_x32(mx);
;             const float mnew = fmaxf(mrun, mx);
;             const float alpha = fast_exp2(mrun - mnew);
;             mrun = mnew;
.LdaB_bias_masked:
	v_add_u32_e32 v0, s89, v201
	s_waitcnt lgkmcnt(14)
	v_pk_add_f32 v[14:15], v[96:97], v[14:15] op_sel:[0,1] op_sel_hi:[1,0]
	ds_read2_b32 v[186:187], v202 offset0:0 offset1:1
	v_cmp_lt_i32_e32 vcc, -1, v0
	v_cmp_lt_i32_e64 s[100:101], 0, v0
	s_nop 1
	v_cndmask_b32_e32 v14, v214, v14, vcc
	v_cndmask_b32_e64 v15, v214, v15, s[100:101]
	s_waitcnt lgkmcnt(14)
	v_pk_add_f32 v[166:167], v[80:81], v[218:219] op_sel:[0,1] op_sel_hi:[1,0]
	v_cmp_lt_i32_e32 vcc, 31, v0
	v_cmp_lt_i32_e64 s[100:101], 32, v0
	s_nop 1
	v_cndmask_b32_e32 v166, v214, v166, vcc
	v_cndmask_b32_e64 v167, v214, v167, s[100:101]
	s_waitcnt lgkmcnt(13)
	v_pk_add_f32 v[148:149], v[98:99], v[220:221] op_sel:[0,1] op_sel_hi:[1,0]
	v_cmp_lt_i32_e32 vcc, 1, v0
	v_cmp_lt_i32_e64 s[100:101], 2, v0
	s_nop 1
	v_cndmask_b32_e32 v148, v214, v148, vcc
	v_cndmask_b32_e64 v149, v214, v149, s[100:101]
	s_waitcnt lgkmcnt(12)
	v_pk_add_f32 v[168:169], v[82:83], v[222:223] op_sel:[0,1] op_sel_hi:[1,0]
	v_cmp_lt_i32_e32 vcc, 33, v0
	v_cmp_lt_i32_e64 s[100:101], 34, v0
	s_nop 1
	v_cndmask_b32_e32 v168, v214, v168, vcc
	v_cndmask_b32_e64 v169, v214, v169, s[100:101]
	s_waitcnt lgkmcnt(11)
	v_pk_add_f32 v[152:153], v[100:101], v[224:225] op_sel:[0,1] op_sel_hi:[1,0]
	v_cmp_lt_i32_e32 vcc, 7, v0
	v_cmp_lt_i32_e64 s[100:101], 8, v0
	s_nop 1
	v_cndmask_b32_e32 v152, v214, v152, vcc
	v_cndmask_b32_e64 v153, v214, v153, s[100:101]
	s_waitcnt lgkmcnt(10)
	v_pk_add_f32 v[174:175], v[84:85], v[174:175] op_sel:[0,1] op_sel_hi:[1,0]
	v_cmp_lt_i32_e32 vcc, 39, v0
	v_cmp_lt_i32_e64 s[100:101], 40, v0
	s_nop 1
	v_cndmask_b32_e32 v174, v214, v174, vcc
	v_cndmask_b32_e64 v175, v214, v175, s[100:101]
	s_waitcnt lgkmcnt(9)
	v_pk_add_f32 v[150:151], v[102:103], v[226:227] op_sel:[0,1] op_sel_hi:[1,0]
	v_cmp_lt_i32_e32 vcc, 9, v0
	v_cmp_lt_i32_e64 s[100:101], 10, v0
	s_nop 1
	v_cndmask_b32_e32 v150, v214, v150, vcc
	v_cndmask_b32_e64 v151, v214, v151, s[100:101]
	s_waitcnt lgkmcnt(8)
	v_pk_add_f32 v[172:173], v[86:87], v[172:173] op_sel:[0,1] op_sel_hi:[1,0]
	v_cmp_lt_i32_e32 vcc, 41, v0
	v_cmp_lt_i32_e64 s[100:101], 42, v0
	s_nop 1
	v_cndmask_b32_e32 v172, v214, v172, vcc
	v_cndmask_b32_e64 v173, v214, v173, s[100:101]
	s_waitcnt lgkmcnt(7)
	v_pk_add_f32 v[170:171], v[104:105], v[242:243] op_sel:[0,1] op_sel_hi:[1,0]
	v_cmp_lt_i32_e32 vcc, 15, v0
	v_cmp_lt_i32_e64 s[100:101], 16, v0
	s_nop 1
	v_cndmask_b32_e32 v170, v214, v170, vcc
	v_cndmask_b32_e64 v171, v214, v171, s[100:101]
	s_waitcnt lgkmcnt(6)
	v_pk_add_f32 v[182:183], v[88:89], v[182:183] op_sel:[0,1] op_sel_hi:[1,0]
	v_cmp_lt_i32_e32 vcc, 47, v0
	v_cmp_lt_i32_e64 s[100:101], 48, v0
	s_nop 1
	v_cndmask_b32_e32 v182, v214, v182, vcc
	v_cndmask_b32_e64 v183, v214, v183, s[100:101]
	s_waitcnt lgkmcnt(5)
	v_pk_add_f32 v[176:177], v[106:107], v[176:177] op_sel:[0,1] op_sel_hi:[1,0]
	v_cmp_lt_i32_e32 vcc, 17, v0
	v_cmp_lt_i32_e64 s[100:101], 18, v0
	s_nop 1
	v_cndmask_b32_e32 v176, v214, v176, vcc
	v_cndmask_b32_e64 v177, v214, v177, s[100:101]
	s_waitcnt lgkmcnt(4)
	v_pk_add_f32 v[184:185], v[90:91], v[184:185] op_sel:[0,1] op_sel_hi:[1,0]
	v_cmp_lt_i32_e32 vcc, 49, v0
	v_cmp_lt_i32_e64 s[100:101], 50, v0
	s_nop 1
	v_cndmask_b32_e32 v184, v214, v184, vcc
	v_cndmask_b32_e64 v185, v214, v185, s[100:101]
	s_waitcnt lgkmcnt(3)
	v_pk_add_f32 v[180:181], v[108:109], v[180:181] op_sel:[0,1] op_sel_hi:[1,0]
	v_cmp_lt_i32_e32 vcc, 23, v0
	v_cmp_lt_i32_e64 s[100:101], 24, v0
	s_nop 1
	v_cndmask_b32_e32 v180, v214, v180, vcc
	v_cndmask_b32_e64 v181, v214, v181, s[100:101]
	s_waitcnt lgkmcnt(2)
	v_pk_add_f32 v[188:189], v[92:93], v[188:189] op_sel:[0,1] op_sel_hi:[1,0]
	v_cmp_lt_i32_e32 vcc, 55, v0
	v_cmp_lt_i32_e64 s[100:101], 56, v0
	s_nop 1
	v_cndmask_b32_e32 v188, v214, v188, vcc
	v_cndmask_b32_e64 v189, v214, v189, s[100:101]
	s_waitcnt lgkmcnt(1)
	v_pk_add_f32 v[178:179], v[110:111], v[178:179] op_sel:[0,1] op_sel_hi:[1,0]
	v_cmp_lt_i32_e32 vcc, 25, v0
	v_cmp_lt_i32_e64 s[100:101], 26, v0
	s_nop 1
	v_cndmask_b32_e32 v178, v214, v178, vcc
	v_cndmask_b32_e64 v179, v214, v179, s[100:101]
	s_waitcnt lgkmcnt(0)
	v_pk_add_f32 v[186:187], v[94:95], v[186:187] op_sel:[0,1] op_sel_hi:[1,0]
	v_cmp_lt_i32_e32 vcc, 57, v0
	v_cmp_lt_i32_e64 s[100:101], 58, v0
	s_nop 1
	v_cndmask_b32_e32 v186, v214, v186, vcc
	v_cndmask_b32_e64 v187, v214, v187, s[100:101]
	v_max_f32_e32 v80, v14, v166
	v_max_f32_e32 v81, v15, v167
	v_max3_f32 v82, v80, s84, v81
	v_max_f32_e32 v80, v148, v168
	v_max_f32_e32 v81, v149, v169
	v_max3_f32 v82, v82, v80, v81
	v_max_f32_e32 v80, v152, v174
	v_max_f32_e32 v81, v153, v175
	v_max3_f32 v82, v82, v80, v81
	v_max_f32_e32 v80, v150, v172
	v_max_f32_e32 v81, v151, v173
	v_max3_f32 v82, v82, v80, v81
	v_max_f32_e32 v80, v170, v182
	v_max_f32_e32 v81, v171, v183
	v_max3_f32 v82, v82, v80, v81
	v_max_f32_e32 v80, v176, v184
	v_max_f32_e32 v81, v177, v185
	v_max3_f32 v82, v82, v80, v81
	v_max_f32_e32 v80, v180, v188
	v_max_f32_e32 v81, v181, v189
	v_max3_f32 v82, v82, v80, v81
	v_max_f32_e32 v80, v178, v186
	v_max_f32_e32 v81, v179, v187
	v_max3_f32 v0, v82, v80, v81
.LBB0_407:
	s_nop 8
	v_mov_b32_e32 v80, v0
	s_nop 1
	v_permlane32_swap_b32_e32 v0, v80
	v_max3_f32 v83, v196, v0, v80
	v_max_f32_e32 v211, v0, v80
	v_sub_f32_e32 v211, v211, v196
	v_cmp_lt_f32_e64 s[100:101], 4.0, v211
	s_nop 1
	s_cmp_eq_u64 s[100:101], 0
	s_cbranch_scc0 .Lresc_keep_B
	v_mov_b32_e32 v83, v196
; __device__ __forceinline__ unsigned cvt_pk_bf16(float lo, float hi) { f32x2_t v = {lo, hi}; bf16x2_t b = __builtin_convertvector(v, bf16x2_t); return __builtin_bit_cast(unsigned, b); }
; __device__ __forceinline__ float fast_exp2(float x) { return __builtin_amdgcn_exp2f(x); }
; template <int MODE> ...
;     ...
;             const float mnew = fmaxf(mrun, mx);
;             const float alpha = fast_exp2(mrun - mnew);
;             mrun = mnew;
;             float ps = 0.f;
; #pragma unroll
;             for (int r = 0; r < 16; ++r) { s0[r] = fast_exp2(s0[r] - mnew); s1[r] = fast_exp2(s1[r] - mnew); ps += s0[r] + s1[r]; }
;             lsum = lsum * alpha + ps;
; #pragma unroll
;             for (int i = 0; i < NDV; ++i)
; #pragma unroll
;                 for (int r = 0; r < 16; ++r) acc[i][r] *= alpha;
;             bf16x8 pf[2][2];
; #pragma unroll
;             for (int t = 0; t < 2; ++t) {
;                 u32x4 w0, w1;
;                 w0.x = cvt_pk_bf16(s0[8 * t + 0], s0[8 * t + 1]); w0.y = cvt_pk_bf16(s0[8 * t + 2], s0[8 * t + 3]); w0.z = cvt_pk_bf16(s0[8 * t + 4], s0[8 * t + 5]); w0.w = cvt_pk_bf16(s0[8 * t + 6], s0[8 * t + 7]);
;                 w1.x = cvt_pk_bf16(s1[8 * t + 0], s1[8 * t + 1]); w1.y = cvt_pk_bf16(s1[8 * t + 2], s1[8 * t + 3]); w1.z = cvt_pk_bf16(s1[8 * t + 4], s1[8 * t + 5]); w1.w = cvt_pk_bf16(s1[8 * t + 6], s1[8 * t + 7]);
;                 pf[0][t] = __builtin_bit_cast(bf16x8, w0); pf[1][t] = __builtin_bit_cast(bf16x8, w1);
;             }
;     ...
;             {
;                 bf16x8 vcur[4], vnxt[4];
;                 AT_LOADV(vcur, 0);
; #pragma unroll
;                 for (int dvb = 0; dvb < NDV; ++dvb) {
;                     if (dvb + 1 < NDV) AT_LOADV(vnxt, dvb + 1);
;                     __builtin_amdgcn_sched_barrier(0);
; #pragma unroll
;                     for (int i = 0; i < 4; ++i) acc[dvb] = __builtin_amdgcn_mfma_f32_32x32x16_bf16(vcur[i], pf[i >> 1][i & 1], acc[dvb], 0, 0, 0);
.Lresc_keep_B:
	v_sub_f32_e32 v85, v152, v83
	v_exp_f32_e32 v152, v85
	v_sub_f32_e32 v85, v174, v83
	v_exp_f32_e32 v155, v85
	v_sub_f32_e32 v85, v153, v83
	v_exp_f32_e32 v88, v85
	v_sub_f32_e32 v85, v175, v83
	v_exp_f32_e32 v86, v85
	v_sub_f32_e32 v85, v150, v83
	v_exp_f32_e32 v150, v85
	v_sub_f32_e32 v85, v172, v83
	v_exp_f32_e32 v153, v85
	v_sub_f32_e32 v85, v151, v83
	v_exp_f32_e32 v92, v85
	v_sub_f32_e32 v85, v173, v83
	v_exp_f32_e32 v90, v85
	v_sub_f32_e32 v85, v170, v83
	v_exp_f32_e32 v151, v85
	v_sub_f32_e32 v85, v182, v83
	v_exp_f32_e32 v156, v85
	v_sub_f32_e32 v85, v171, v83
	v_exp_f32_e32 v96, v85
	v_sub_f32_e32 v85, v183, v83
	v_exp_f32_e32 v94, v85
	v_sub_f32_e32 v85, v176, v83
	v_exp_f32_e32 v157, v85
	v_sub_f32_e32 v85, v184, v83
	v_exp_f32_e32 v158, v85
	v_sub_f32_e32 v85, v177, v83
	v_sub_f32_e32 v0, v14, v83
	v_exp_f32_e32 v100, v85
	v_sub_f32_e32 v85, v185, v83
	v_exp_f32_e32 v110, v0
	v_sub_f32_e32 v0, v166, v83
	v_sub_f32_e32 v14, v167, v83
	v_exp_f32_e32 v98, v85
	v_sub_f32_e32 v85, v180, v83
	v_exp_f32_e32 v137, v0
	v_sub_f32_e32 v0, v15, v83
	v_exp_f32_e32 v80, v14
	v_sub_f32_e32 v14, v148, v83
	v_exp_f32_e32 v159, v85
	v_sub_f32_e32 v85, v188, v83
	v_exp_f32_e32 v0, v0
	v_exp_f32_e32 v111, v14
	v_sub_f32_e32 v14, v168, v83
	v_exp_f32_e32 v160, v85
	v_sub_f32_e32 v85, v181, v83
	v_exp_f32_e32 v154, v14
	v_sub_f32_e32 v14, v149, v83
	v_exp_f32_e32 v104, v85
	v_sub_f32_e32 v85, v189, v83
	v_exp_f32_e32 v84, v14
	v_sub_f32_e32 v14, v169, v83
	v_exp_f32_e32 v102, v85
	v_sub_f32_e32 v85, v178, v83
	v_add_f32_e32 v81, v137, v110
	v_exp_f32_e32 v14, v14
	v_exp_f32_e32 v161, v85
	v_sub_f32_e32 v85, v186, v83
	v_exp_f32_e32 v162, v85
	v_sub_f32_e32 v85, v179, v83
	v_pk_add_f32 v[108:109], v[80:81], v[0:1]
	v_exp_f32_e32 v148, v85
	v_sub_f32_e32 v85, v187, v83
	v_pk_add_f32 v[108:109], v[108:109], v[108:109] op_sel_hi:[0,1]
	v_add_f32_e32 v15, v154, v111
	v_exp_f32_e32 v106, v85
	v_mov_b32_e32 v85, v109
	v_pk_add_f32 v[108:109], v[14:15], v[84:85]
	v_add_f32_e32 v87, v155, v152
	v_pk_add_f32 v[108:109], v[108:109], v[108:109] op_sel_hi:[0,1]
	v_mov_b32_e32 v89, v109
	v_pk_add_f32 v[108:109], v[86:87], v[88:89]
	v_add_f32_e32 v91, v153, v150
	v_pk_add_f32 v[108:109], v[108:109], v[108:109] op_sel_hi:[0,1]
	v_mov_b32_e32 v93, v109
	v_pk_add_f32 v[108:109], v[90:91], v[92:93]
	v_add_f32_e32 v95, v156, v151
	v_pk_add_f32 v[108:109], v[108:109], v[108:109] op_sel_hi:[0,1]
	v_mov_b32_e32 v97, v109
	v_pk_add_f32 v[108:109], v[94:95], v[96:97]
	v_add_f32_e32 v99, v158, v157
	v_pk_add_f32 v[108:109], v[108:109], v[108:109] op_sel_hi:[0,1]
	v_mov_b32_e32 v101, v109
	v_pk_add_f32 v[108:109], v[98:99], v[100:101]
	v_add_f32_e32 v103, v160, v159
	v_pk_add_f32 v[108:109], v[108:109], v[108:109] op_sel_hi:[0,1]
	v_mov_b32_e32 v105, v109
	v_pk_add_f32 v[108:109], v[102:103], v[104:105]
	v_add_f32_e32 v107, v162, v161
	v_pk_add_f32 v[108:109], v[108:109], v[108:109] op_sel_hi:[0,1]
	v_mov_b32_e32 v149, v109
	v_pk_add_f32 v[108:109], v[106:107], v[148:149]
	v_cvt_pk_bf16_f32 v87, v153, v90
	v_add_f32_e32 v15, v108, v109
	v_cvt_pk_bf16_f32 v108, v110, v0
	v_add3_u32 v0, s12, v194, v141
	v_add_u32_e32 v0, 0x4000, v0
	v_cvt_pk_bf16_f32 v109, v111, v84
	v_cvt_pk_bf16_f32 v110, v152, v88
	v_cvt_pk_bf16_f32 v111, v150, v92
	v_cvt_pk_bf16_f32 v88, v151, v96
	v_cvt_pk_bf16_f32 v89, v157, v100
	v_cvt_pk_bf16_f32 v90, v159, v104
	v_cvt_pk_bf16_f32 v91, v161, v148
	v_cvt_pk_bf16_f32 v92, v156, v94
	v_cvt_pk_bf16_f32 v93, v158, v98
	v_cvt_pk_bf16_f32 v94, v160, v102
	v_cvt_pk_bf16_f32 v95, v162, v106
	ds_read2_b64 v[96:99], v0 offset0:128 offset1:130
	ds_read2_b64 v[100:103], v0 offset0:132 offset1:134
	ds_read2_b64 v[104:107], v0 offset0:136 offset1:138
	ds_read2_b64 v[148:151], v0 offset0:140 offset1:142
	v_add3_u32 v0, s12, v141, v194
	v_cvt_pk_bf16_f32 v85, v154, v14
	v_add_u32_e32 v14, 0x5000, v0
	v_cvt_pk_bf16_f32 v86, v155, v86
	ds_read2_b64 v[152:155], v14 offset0:160 offset1:162
	ds_read2_b64 v[156:159], v14 offset0:164 offset1:166
	ds_read2_b64 v[160:163], v14 offset0:168 offset1:170
	ds_read2_b64 v[164:167], v14 offset0:172 offset1:174
	v_sub_f32_e32 v82, v196, v83
	v_exp_f32_e32 v82, v82
	v_cvt_pk_bf16_f32 v84, v137, v80
	s_cmp_eq_u64 s[100:101], 0
	s_cbranch_scc1 .Lresc_skip_B
	v_pk_mul_f32 v[78:79], v[78:79], v[82:83] op_sel_hi:[1,0]
	v_pk_mul_f32 v[76:77], v[76:77], v[82:83] op_sel_hi:[1,0]
	v_pk_mul_f32 v[74:75], v[74:75], v[82:83] op_sel_hi:[1,0]
	v_pk_mul_f32 v[72:73], v[72:73], v[82:83] op_sel_hi:[1,0]
	v_pk_mul_f32 v[70:71], v[70:71], v[82:83] op_sel_hi:[1,0]
	v_pk_mul_f32 v[68:69], v[68:69], v[82:83] op_sel_hi:[1,0]
	v_pk_mul_f32 v[66:67], v[66:67], v[82:83] op_sel_hi:[1,0]
	v_pk_mul_f32 v[64:65], v[64:65], v[82:83] op_sel_hi:[1,0]
	v_pk_mul_f32 v[62:63], v[62:63], v[82:83] op_sel_hi:[1,0]
	v_pk_mul_f32 v[60:61], v[60:61], v[82:83] op_sel_hi:[1,0]
	v_pk_mul_f32 v[58:59], v[58:59], v[82:83] op_sel_hi:[1,0]
	v_pk_mul_f32 v[56:57], v[56:57], v[82:83] op_sel_hi:[1,0]
	v_pk_mul_f32 v[54:55], v[54:55], v[82:83] op_sel_hi:[1,0]
	v_pk_mul_f32 v[52:53], v[52:53], v[82:83] op_sel_hi:[1,0]
	v_pk_mul_f32 v[50:51], v[50:51], v[82:83] op_sel_hi:[1,0]
	v_pk_mul_f32 v[48:49], v[48:49], v[82:83] op_sel_hi:[1,0]
	v_pk_mul_f32 v[46:47], v[46:47], v[82:83] op_sel_hi:[1,0]
	v_pk_mul_f32 v[44:45], v[44:45], v[82:83] op_sel_hi:[1,0]
	v_pk_mul_f32 v[42:43], v[42:43], v[82:83] op_sel_hi:[1,0]
	v_pk_mul_f32 v[40:41], v[40:41], v[82:83] op_sel_hi:[1,0]
	v_pk_mul_f32 v[38:39], v[38:39], v[82:83] op_sel_hi:[1,0]
	v_pk_mul_f32 v[36:37], v[36:37], v[82:83] op_sel_hi:[1,0]
	v_pk_mul_f32 v[34:35], v[34:35], v[82:83] op_sel_hi:[1,0]
	v_pk_mul_f32 v[32:33], v[32:33], v[82:83] op_sel_hi:[1,0]
	v_pk_mul_f32 v[30:31], v[30:31], v[82:83] op_sel_hi:[1,0]
	v_pk_mul_f32 v[28:29], v[28:29], v[82:83] op_sel_hi:[1,0]
	v_pk_mul_f32 v[26:27], v[26:27], v[82:83] op_sel_hi:[1,0]
	v_pk_mul_f32 v[24:25], v[24:25], v[82:83] op_sel_hi:[1,0]
	v_pk_mul_f32 v[22:23], v[22:23], v[82:83] op_sel_hi:[1,0]
	v_pk_mul_f32 v[20:21], v[20:21], v[82:83] op_sel_hi:[1,0]
	v_pk_mul_f32 v[18:19], v[18:19], v[82:83] op_sel_hi:[1,0]
	v_pk_mul_f32 v[16:17], v[16:17], v[82:83] op_sel_hi:[1,0]
; template <int MODE> ...
;     ...
;             {
;                 bf16x8 vcur[4], vnxt[4];
;                 AT_LOADV(vcur, 0);
; #pragma unroll
;                 for (int dvb = 0; dvb < NDV; ++dvb) {
;                     if (dvb + 1 < NDV) AT_LOADV(vnxt, dvb + 1);
;                     __builtin_amdgcn_sched_barrier(0);
; #pragma unroll
;                     for (int i = 0; i < 4; ++i) acc[dvb] = __builtin_amdgcn_mfma_f32_32x32x16_bf16(vcur[i], pf[i >> 1][i & 1], acc[dvb], 0, 0, 0);
;                     __builtin_amdgcn_sched_barrier(0);
; #pragma unroll
;                     for (int i = 0; i < 4; ++i) vcur[i] = vnxt[i];
;                 }
.Lresc_skip_B:
	s_waitcnt lgkmcnt(7)
	v_mfma_f32_32x32x16_bf16 v[64:79], v[96:99], v[108:111], v[64:79]
	s_waitcnt lgkmcnt(6)
	v_mfma_f32_32x32x16_bf16 v[64:79], v[100:103], v[88:91], v[64:79]
	s_waitcnt lgkmcnt(5)
	v_mfma_f32_32x32x16_bf16 v[64:79], v[104:107], v[84:87], v[64:79]
	s_waitcnt lgkmcnt(4)
	v_mfma_f32_32x32x16_bf16 v[64:79], v[148:151], v[92:95], v[64:79]
	v_add_u32_e32 v14, 0x6000, v0
	ds_read2_b64 v[96:99], v14 offset0:192 offset1:194
	ds_read2_b64 v[100:103], v14 offset0:196 offset1:198
	ds_read2_b64 v[104:107], v14 offset0:200 offset1:202
	ds_read2_b64 v[148:151], v14 offset0:204 offset1:206
	s_waitcnt lgkmcnt(7)
	v_mfma_f32_32x32x16_bf16 v[48:63], v[152:155], v[108:111], v[48:63]
	s_waitcnt lgkmcnt(6)
	v_mfma_f32_32x32x16_bf16 v[48:63], v[156:159], v[88:91], v[48:63]
	s_waitcnt lgkmcnt(5)
	v_mfma_f32_32x32x16_bf16 v[48:63], v[160:163], v[84:87], v[48:63]
	s_waitcnt lgkmcnt(4)
	v_mfma_f32_32x32x16_bf16 v[48:63], v[164:167], v[92:95], v[48:63]
	v_add_u32_e32 v0, 0x7000, v0
	ds_read2_b64 v[152:155], v0 offset0:224 offset1:226
	ds_read2_b64 v[156:159], v0 offset0:228 offset1:230
	ds_read2_b64 v[160:163], v0 offset0:232 offset1:234
	ds_read2_b64 v[164:167], v0 offset0:236 offset1:238
	s_waitcnt lgkmcnt(7)
	v_mfma_f32_32x32x16_bf16 v[32:47], v[96:99], v[108:111], v[32:47]
	s_waitcnt lgkmcnt(6)
	v_mfma_f32_32x32x16_bf16 v[32:47], v[100:103], v[88:91], v[32:47]
	s_waitcnt lgkmcnt(5)
	v_mfma_f32_32x32x16_bf16 v[32:47], v[104:107], v[84:87], v[32:47]
	s_waitcnt lgkmcnt(4)
	v_mfma_f32_32x32x16_bf16 v[32:47], v[148:151], v[92:95], v[32:47]
	s_waitcnt lgkmcnt(3)
	v_mfma_f32_32x32x16_bf16 v[16:31], v[152:155], v[108:111], v[16:31]
	s_waitcnt lgkmcnt(2)
	v_mfma_f32_32x32x16_bf16 v[16:31], v[156:159], v[88:91], v[16:31]
	s_waitcnt lgkmcnt(1)
	v_mfma_f32_32x32x16_bf16 v[16:31], v[160:163], v[84:87], v[16:31]
	s_waitcnt lgkmcnt(0)
	v_mfma_f32_32x32x16_bf16 v[16:31], v[164:167], v[92:95], v[16:31]
	v_fmac_f32_e32 v15, v139, v82
	v_mov_b32_e32 v196, v83
	v_mov_b32_e32 v139, v15
